# v030 + non-temporal hint on the ret_state chunk-state stores
# baseline (speedup 1.0000x reference)
; #define MFMA32(a, b, c) __builtin_amdgcn_mfma_f32_32x32x16_bf16((a), (b), (c), 0, 0, 0)
; __device__ __forceinline__ v4u pk8(const f32x16& o, int b) { v4u w; w.x = cvt_pk_bf16(o[b], o[b + 1]); w.y = cvt_pk_bf16(o[b + 2], o[b + 3]); w.z = cvt_pk_bf16(o[b + 4], o[b + 5]); w.w = cvt_pk_bf16(o[b + 6], o[b + 7]); return w; }
; __device__ __forceinline__ void phase_ret_state(const Frame& F, const Args& a, int l) {
;     ...
;         for (int st = 0; st < 32; ++st) {
;             const int n = z ? (31 - st) : st; const int st1 = st < 31 ? st + 1 : 31, nn = z ? (31 - st1) : st1;
;             bf16* sp = srow + (size_t)n * 65536;
;             *(v4u*)sp = pk8(acc0, 0); *(v4u*)(sp + 512) = pk8(acc0, 8); *(v4u*)(sp + 1024) = pk8(acc1, 0); *(v4u*)(sp + 1536) = pk8(acc1, 8);
; #pragma unroll
;             for (int e = 0; e < 16; ++e) { acc0[e] *= g; acc1[e] *= g; }
; #pragma unroll
;             for (int ks = 0; ks < 8; ++ks) acc0 = MFMA32(kfa[ks], vf[ks], acc0);
; #pragma unroll
;             for (int ks = 0; ks < 8; ++ks) kfa[ks] = *(const bf16x8*)(krow + 4096 * nn + 512 * ks);
; #pragma unroll
;             for (int ks = 0; ks < 8; ++ks) acc1 = MFMA32(kfb[ks], vf[ks], acc1);
; #pragma unroll
;             for (int ks = 0; ks < 8; ++ks) { kfb[ks] = *(const bf16x8*)(krow + (size_t)(T / 16) * 512 + 4096 * nn + 512 * ks); vf[ks] = *(const bf16x8*)(vrow + 4096 * nn + 512 * ks); }
;         }
.Lrs_loop:
	s_min_u32 s17, s16, 31
	s_sub_i32 s18, 31, s17
	s_add_i32 s20, s16, -1
	s_sub_i32 s21, 31, s20
	s_and_b64 s[10:11], s[4:5], exec
	s_cselect_b32 s10, s17, s18
	s_cselect_b32 s18, s20, s21
	s_lshl_b32 s10, s10, 13
	s_mov_b32 s11, 0
	s_lshl_b32 s18, s18, 17
	s_mov_b32 s19, 0
	v_lshl_add_u64 v[96:97], v[46:47], 0, s[10:11]
	v_lshl_add_u64 v[94:95], v[48:49], 0, s[10:11]
	v_lshl_add_u64 v[92:93], v[50:51], 0, s[10:11]
	v_lshl_add_u64 v[90:91], v[96:97], 0, s[24:25]
	v_lshl_add_u64 v[88:89], v[94:95], 0, s[24:25]
	v_lshl_add_u64 v[86:87], v[92:93], 0, s[24:25]
	v_lshl_add_u64 v[68:69], v[52:53], 0, s[18:19]
	v_cvt_pk_bf16_f32 v32, v0, v1
	v_cvt_pk_bf16_f32 v33, v2, v3
	v_cvt_pk_bf16_f32 v34, v4, v5
	v_cvt_pk_bf16_f32 v35, v6, v7
	v_cvt_pk_bf16_f32 v36, v8, v9
	v_cvt_pk_bf16_f32 v37, v10, v11
	v_cvt_pk_bf16_f32 v38, v12, v13
	v_cvt_pk_bf16_f32 v39, v14, v15
	v_pk_mul_f32 v[0:1], v[56:57], v[0:1]
	v_pk_mul_f32 v[2:3], v[54:55], v[2:3]
	v_pk_mul_f32 v[4:5], v[54:55], v[4:5]
	v_pk_mul_f32 v[6:7], v[54:55], v[6:7]
	v_pk_mul_f32 v[8:9], v[54:55], v[8:9]
	v_pk_mul_f32 v[10:11], v[54:55], v[10:11]
	v_pk_mul_f32 v[12:13], v[54:55], v[12:13]
	v_pk_mul_f32 v[14:15], v[54:55], v[14:15]
	v_cvt_pk_bf16_f32 v60, v16, v17
	v_cvt_pk_bf16_f32 v61, v18, v19
	v_cvt_pk_bf16_f32 v62, v20, v21
	v_cvt_pk_bf16_f32 v63, v22, v23
	v_cvt_pk_bf16_f32 v64, v24, v25
	v_cvt_pk_bf16_f32 v65, v26, v27
	v_cvt_pk_bf16_f32 v66, v28, v29
	v_cvt_pk_bf16_f32 v67, v30, v31
	v_pk_mul_f32 v[16:17], v[56:57], v[16:17]
	v_pk_mul_f32 v[18:19], v[54:55], v[18:19]
	v_pk_mul_f32 v[20:21], v[54:55], v[20:21]
	v_pk_mul_f32 v[22:23], v[54:55], v[22:23]
	v_pk_mul_f32 v[24:25], v[54:55], v[24:25]
	v_pk_mul_f32 v[26:27], v[54:55], v[26:27]
	v_pk_mul_f32 v[28:29], v[54:55], v[28:29]
	v_pk_mul_f32 v[30:31], v[54:55], v[30:31]
	global_store_dwordx4 v[68:69], v[32:35], off nt
	global_store_dwordx4 v[68:69], v[36:39], off offset:1024 nt
	global_store_dwordx4 v[68:69], v[60:63], off offset:2048 nt
	global_store_dwordx4 v[68:69], v[64:67], off offset:3072 nt
	s_waitcnt vmcnt(25)
	v_mfma_f32_32x32x16_bf16 v[0:15], v[100:103], v[168:171], v[0:15]
	v_mfma_f32_32x32x16_bf16 v[16:31], v[136:139], v[168:171], v[16:31]
	global_load_dwordx4 v[100:103], v[96:97], off
	global_load_dwordx4 v[168:171], v[92:93], off
	global_load_dwordx4 v[136:139], v[94:95], off
	s_waitcnt vmcnt(25)
	v_mfma_f32_32x32x16_bf16 v[0:15], v[104:107], v[172:175], v[0:15]
	v_mfma_f32_32x32x16_bf16 v[16:31], v[140:143], v[172:175], v[16:31]
	global_load_dwordx4 v[104:107], v[96:97], off offset:1024
	global_load_dwordx4 v[172:175], v[92:93], off offset:1024
	global_load_dwordx4 v[140:143], v[94:95], off offset:1024
	s_waitcnt vmcnt(25)
	v_mfma_f32_32x32x16_bf16 v[0:15], v[108:111], v[176:179], v[0:15]
	v_mfma_f32_32x32x16_bf16 v[16:31], v[144:147], v[176:179], v[16:31]
	global_load_dwordx4 v[108:111], v[96:97], off offset:2048
	global_load_dwordx4 v[176:179], v[92:93], off offset:2048
	global_load_dwordx4 v[144:147], v[94:95], off offset:2048
	s_waitcnt vmcnt(25)
	v_mfma_f32_32x32x16_bf16 v[0:15], v[112:115], v[180:183], v[0:15]
	v_mfma_f32_32x32x16_bf16 v[16:31], v[148:151], v[180:183], v[16:31]
	global_load_dwordx4 v[112:115], v[96:97], off offset:3072
	global_load_dwordx4 v[180:183], v[92:93], off offset:3072
	global_load_dwordx4 v[148:151], v[94:95], off offset:3072
	s_waitcnt vmcnt(25)
	v_mfma_f32_32x32x16_bf16 v[0:15], v[116:119], v[188:191], v[0:15]
	v_mfma_f32_32x32x16_bf16 v[16:31], v[152:155], v[188:191], v[16:31]
	global_load_dwordx4 v[116:119], v[90:91], off
	global_load_dwordx4 v[188:191], v[86:87], off
	global_load_dwordx4 v[152:155], v[88:89], off
	s_waitcnt vmcnt(25)
	v_mfma_f32_32x32x16_bf16 v[0:15], v[120:123], v[192:195], v[0:15]
	v_mfma_f32_32x32x16_bf16 v[16:31], v[156:159], v[192:195], v[16:31]
	global_load_dwordx4 v[120:123], v[90:91], off offset:1024
	global_load_dwordx4 v[192:195], v[86:87], off offset:1024
	global_load_dwordx4 v[156:159], v[88:89], off offset:1024
	s_waitcnt vmcnt(25)
	v_mfma_f32_32x32x16_bf16 v[0:15], v[124:127], v[196:199], v[0:15]
	v_mfma_f32_32x32x16_bf16 v[16:31], v[160:163], v[196:199], v[16:31]
	global_load_dwordx4 v[124:127], v[90:91], off offset:2048
	global_load_dwordx4 v[196:199], v[86:87], off offset:2048
	global_load_dwordx4 v[160:163], v[88:89], off offset:2048
	s_waitcnt vmcnt(25)
	v_mfma_f32_32x32x16_bf16 v[0:15], v[132:135], v[200:203], v[0:15]
	v_mfma_f32_32x32x16_bf16 v[16:31], v[164:167], v[200:203], v[16:31]
	global_load_dwordx4 v[132:135], v[90:91], off offset:3072
	global_load_dwordx4 v[200:203], v[86:87], off offset:3072
	global_load_dwordx4 v[164:167], v[88:89], off offset:3072
	s_add_i32 s16, s16, 1
	s_cmp_le_u32 s16, 32
	s_cbranch_scc1 .Lrs_loop
	s_add_i32 s12, s12, s15
	s_cmpk_gt_i32 s12, 0x4ff
	s_cbranch_scc0 .LBB0_1151
